# exact counted waits at the attention loop back-edge (the LSE store is always issued: lanes 0-31 of every wave): vmcnt 7/6/5/4 -> 8/7/6/5; plus dead barrier relay atomic removed
# speedup vs baseline: 1.0017x; 1.0017x over previous
; __device__ __forceinline__ void attn_phase_mfma(const Ctx& c, unsigned char* lds_raw, bool do_store) {
;     ...
;         __syncthreads();
;         if (un >= NAT) break;
;         u = un;
;     }
.LBB0_358:
	s_or_b64 exec, exec, s[0:1]
	s_add_i32 s4, s4, s5
	s_waitcnt vmcnt(8)
	v_mov_b64_e32 v[10:11], v[142:143]
	s_waitcnt vmcnt(7)
	v_mov_b64_e32 v[2:3], v[138:139]
	s_waitcnt vmcnt(6)
	v_mov_b64_e32 v[14:15], v[134:135]
	s_waitcnt vmcnt(5)
	v_mov_b64_e32 v[6:7], v[130:131]
	s_cmpk_lt_i32 s33, 0x600
	v_mov_b64_e32 v[12:13], v[144:145]
	v_mov_b64_e32 v[4:5], v[140:141]
	v_mov_b64_e32 v[16:17], v[136:137]
	v_mov_b64_e32 v[8:9], v[132:133]
	s_barrier
	s_cbranch_scc0 .LBB0_381
